# SGU: 8 bias loads hoisted before output loop, removed 7 serialized vmcnt(0) store-ack waits
# baseline (speedup 1.0000x reference)
.LBB0_825:
	s_ashr_i32 s8, s65, 7
	v_mov_b32_e32 v130, v217
	s_ashr_i32 s9, s8, 31
	v_ashrrev_i32_e32 v0, 2, v130
	s_lshl_b64 s[36:37], s[8:9], 12
	s_and_b32 s7, s64, 0xf80
	v_add_u32_e32 v44, s10, v0
	s_or_b32 s36, s36, s7
	v_ashrrev_i32_e32 v45, 31, v44
	v_lshl_add_u64 v[0:1], s[36:37], 0, v[44:45]
	v_mov_b64_e32 v[2:3], s[82:83]
	v_mad_u64_u32 v[2:3], s[8:9], v0, s14, v[2:3]
	v_lshlrev_b32_e32 v0, 3, v130
	v_and_b32_e32 v45, 24, v0
	v_mad_i32_i24 v3, v1, s14, v3
	v_lshlrev_b32_e32 v194, 1, v45
	v_lshl_add_u64 v[0:1], v[2:3], 0, v[194:195]
	v_lshl_add_u64 v[2:3], v[0:1], 0, s[66:67]
	v_add_co_u32_e32 v0, vcc, s15, v0
	v_mov_b32_e32 v100, v195
	s_nop 0
	v_addc_co_u32_e32 v1, vcc, 0, v1, vcc
	global_load_dwordx4 v[46:49], v[0:1], off offset:1024
	global_load_dwordx4 v[50:53], v[2:3], off offset:64
	global_load_dwordx4 v[54:57], v[2:3], off offset:128
	global_load_dwordx4 v[60:63], v[2:3], off offset:192
	global_load_dwordx4 v[68:71], v[2:3], off offset:256
	global_load_dwordx4 v[72:75], v[2:3], off offset:320
	global_load_dwordx4 v[76:79], v[2:3], off offset:384
	global_load_dwordx4 v[80:83], v[2:3], off offset:448
	global_load_dwordx4 v[110:113], v[2:3], off offset:512
	global_load_dwordx4 v[40:43], v[2:3], off offset:576
	global_load_dwordx4 v[36:39], v[2:3], off offset:640
	global_load_dwordx4 v[32:35], v[2:3], off offset:704
	global_load_dwordx4 v[28:31], v[2:3], off offset:768
	global_load_dwordx4 v[24:27], v[2:3], off offset:832
	global_load_dwordx4 v[20:23], v[2:3], off offset:896
	global_load_dwordx4 v[16:19], v[2:3], off offset:960
	s_and_b32 s45, s65, 3
	s_lshl_b32 s60, s45, 7
	s_lshl_b32 s92, s45, 8
	s_lshl_b32 s7, s45, 9
	s_add_u32 s40, s12, s7
	s_addc_u32 s41, s16, 0
	v_lshl_add_u64 v[0:1], v[2:3], 0, s[92:93]
	s_add_u32 s46, s17, s7
	global_load_dwordx4 v[12:15], v[0:1], off
	global_load_dwordx4 v[8:11], v[0:1], off offset:64
	global_load_dwordx4 v[4:7], v[0:1], off offset:128
	s_nop 0
	global_load_dwordx4 v[0:3], v[0:1], off offset:192
	s_addc_u32 s47, s18, 0
	s_add_u32 s8, s33, s92
	v_and_b32_e32 v132, 15, v130
	s_addc_u32 s9, s34, 0
	s_lshl_b32 s7, s45, 15
	v_lshlrev_b32_e32 v194, 8, v132
	s_waitcnt vmcnt(19)
	v_lshlrev_b32_e32 v115, 16, v48
	v_lshlrev_b32_e32 v114, 16, v46
	v_and_b32_e32 v117, 0xffff0000, v48
	v_and_b32_e32 v116, 0xffff0000, v46
	v_lshlrev_b32_e32 v119, 16, v49
	v_lshlrev_b32_e32 v118, 16, v47
	v_and_b32_e32 v121, 0xffff0000, v49
	v_and_b32_e32 v120, 0xffff0000, v47
	v_pk_add_f32 v[58:59], v[114:115], v[116:117]
	v_pk_add_f32 v[46:47], v[118:119], v[120:121]
	s_waitcnt vmcnt(18)
	v_lshlrev_b32_e32 v109, 16, v51
	v_lshlrev_b32_e32 v108, 16, v50
	v_and_b32_e32 v107, 0xffff0000, v51
	v_and_b32_e32 v106, 0xffff0000, v50
	v_lshlrev_b32_e32 v105, 16, v53
	v_lshlrev_b32_e32 v104, 16, v52
	v_and_b32_e32 v103, 0xffff0000, v53
	v_and_b32_e32 v102, 0xffff0000, v52
	v_pk_add_f32 v[46:47], v[58:59], v[46:47]
	v_pk_add_f32 v[48:49], v[108:109], v[106:107]
	v_pk_add_f32 v[50:51], v[104:105], v[102:103]
	s_waitcnt vmcnt(16)
	v_lshlrev_b32_e32 v142, 16, v60
	v_lshlrev_b32_e32 v143, 16, v61
	v_and_b32_e32 v144, 0xffff0000, v61
	v_pk_add_f32 v[46:47], v[46:47], v[46:47] op_sel:[0,1] op_sel_hi:[1,0]
	v_pk_add_f32 v[48:49], v[48:49], v[48:49] op_sel:[0,1] op_sel_hi:[1,0]
	v_pk_add_f32 v[50:51], v[50:51], v[50:51] op_sel:[0,1] op_sel_hi:[1,0]
	v_lshlrev_b32_e32 v131, 16, v54
	v_and_b32_e32 v133, 0xffff0000, v54
	v_lshlrev_b32_e32 v136, 16, v55
	v_and_b32_e32 v137, 0xffff0000, v55
	v_lshlrev_b32_e32 v138, 16, v56
	v_and_b32_e32 v139, 0xffff0000, v56
	v_lshlrev_b32_e32 v140, 16, v57
	v_and_b32_e32 v141, 0xffff0000, v57
	v_and_b32_e32 v101, 0xffff0000, v60
	v_mov_b32_e32 v47, v142
	v_mov_b32_e32 v49, v143
	v_mov_b32_e32 v51, v144
	v_add_f32_e32 v54, v131, v133
	v_add_f32_e32 v58, v136, v137
	v_add_f32_e32 v64, v138, v139
	v_add_f32_e32 v66, v140, v141
	v_lshlrev_b32_e32 v55, 16, v62
	v_and_b32_e32 v59, 0xffff0000, v62
	v_lshlrev_b32_e32 v65, 16, v63
	v_and_b32_e32 v67, 0xffff0000, v63
	v_pk_add_f32 v[46:47], v[46:47], v[100:101]
	v_pk_add_f32 v[48:49], v[48:49], v[50:51]
	v_pk_add_f32 v[50:51], v[64:65], v[66:67]
	v_pk_add_f32 v[46:47], v[46:47], v[48:49]
	v_pk_add_f32 v[48:49], v[54:55], v[58:59]
	s_waitcnt vmcnt(15)
	v_lshlrev_b32_e32 v95, 16, v70
	v_pk_add_f32 v[48:49], v[48:49], v[50:51]
	v_lshlrev_b32_e32 v94, 16, v68
	v_and_b32_e32 v93, 0xffff0000, v70
	v_and_b32_e32 v92, 0xffff0000, v68
	v_lshlrev_b32_e32 v99, 16, v71
	v_lshlrev_b32_e32 v98, 16, v69
	v_and_b32_e32 v97, 0xffff0000, v71
	v_and_b32_e32 v96, 0xffff0000, v69
	v_pk_add_f32 v[56:57], v[46:47], v[48:49]
	v_pk_add_f32 v[46:47], v[94:95], v[92:93]
	v_pk_add_f32 v[48:49], v[98:99], v[96:97]
	s_waitcnt vmcnt(14)
	v_lshlrev_b32_e32 v91, 16, v73
	v_pk_add_f32 v[60:61], v[46:47], v[48:49]
	v_lshlrev_b32_e32 v90, 16, v72
	v_and_b32_e32 v89, 0xffff0000, v73
	v_and_b32_e32 v88, 0xffff0000, v72
	v_lshlrev_b32_e32 v87, 16, v75
	v_lshlrev_b32_e32 v86, 16, v74
	v_and_b32_e32 v85, 0xffff0000, v75
	v_and_b32_e32 v84, 0xffff0000, v74
	s_waitcnt vmcnt(12)
	v_lshlrev_b32_e32 v148, 16, v80
	v_and_b32_e32 v149, 0xffff0000, v80
	v_pk_add_f32 v[56:57], v[56:57], v[56:57] op_sel:[0,1] op_sel_hi:[1,0]
	v_pk_add_f32 v[60:61], v[60:61], v[60:61] op_sel:[0,1] op_sel_hi:[1,0]
	v_pk_add_f32 v[62:63], v[90:91], v[88:89]
	v_pk_add_f32 v[68:69], v[86:87], v[84:85]
	v_mov_b32_e32 v57, v148
	v_mov_b32_e32 v61, v149
	v_lshlrev_b32_e32 v150, 16, v81
	v_and_b32_e32 v151, 0xffff0000, v81
	v_pk_add_f32 v[56:57], v[56:57], v[60:61]
	v_pk_add_f32 v[60:61], v[62:63], v[62:63] op_sel:[0,1] op_sel_hi:[1,0]
	v_pk_add_f32 v[62:63], v[68:69], v[68:69] op_sel:[0,1] op_sel_hi:[1,0]
	v_lshlrev_b32_e32 v54, 16, v76
	v_and_b32_e32 v58, 0xffff0000, v76
	v_lshlrev_b32_e32 v64, 16, v77
	v_and_b32_e32 v66, 0xffff0000, v77
	v_lshlrev_b32_e32 v100, 16, v78
	v_and_b32_e32 v145, 0xffff0000, v78
	v_lshlrev_b32_e32 v146, 16, v79
	v_and_b32_e32 v147, 0xffff0000, v79
	v_mov_b32_e32 v61, v150
	v_mov_b32_e32 v63, v151
	v_add_f32_e32 v46, v54, v58
	v_add_f32_e32 v48, v64, v66
	v_add_f32_e32 v50, v100, v145
	v_add_f32_e32 v52, v146, v147
	v_lshlrev_b32_e32 v47, 16, v82
	v_and_b32_e32 v49, 0xffff0000, v82
	v_lshlrev_b32_e32 v51, 16, v83
	v_and_b32_e32 v53, 0xffff0000, v83
	v_pk_add_f32 v[60:61], v[60:61], v[62:63]
	v_pk_add_f32 v[62:63], v[50:51], v[52:53]
	v_pk_add_f32 v[56:57], v[56:57], v[60:61]
	v_pk_add_f32 v[60:61], v[46:47], v[48:49]
	s_waitcnt vmcnt(11)
	v_lshlrev_b32_e32 v79, 16, v112
	v_pk_add_f32 v[60:61], v[60:61], v[62:63]
	v_lshlrev_b32_e32 v78, 16, v110
	v_and_b32_e32 v77, 0xffff0000, v112
	v_and_b32_e32 v76, 0xffff0000, v110
	v_lshlrev_b32_e32 v83, 16, v113
	v_lshlrev_b32_e32 v82, 16, v111
	v_and_b32_e32 v81, 0xffff0000, v113
	v_and_b32_e32 v80, 0xffff0000, v111
	v_pk_add_f32 v[56:57], v[56:57], v[60:61]
	v_pk_add_f32 v[60:61], v[78:79], v[76:77]
	v_pk_add_f32 v[62:63], v[82:83], v[80:81]
	s_waitcnt vmcnt(10)
	v_lshlrev_b32_e32 v75, 16, v41
	v_pk_add_f32 v[60:61], v[60:61], v[62:63]
	v_lshlrev_b32_e32 v74, 16, v40
	v_and_b32_e32 v73, 0xffff0000, v41
	v_and_b32_e32 v72, 0xffff0000, v40
	v_lshlrev_b32_e32 v71, 16, v43
	v_lshlrev_b32_e32 v70, 16, v42
	v_and_b32_e32 v69, 0xffff0000, v43
	v_and_b32_e32 v68, 0xffff0000, v42
	s_waitcnt vmcnt(9)
	v_lshlrev_b32_e32 v50, 16, v37
	v_and_b32_e32 v52, 0xffff0000, v37
	v_lshlrev_b32_e32 v154, 16, v39
	v_and_b32_e32 v155, 0xffff0000, v39
	s_waitcnt vmcnt(8)
	v_lshlrev_b32_e32 v156, 16, v32
	v_and_b32_e32 v157, 0xffff0000, v32
	v_lshlrev_b32_e32 v158, 16, v33
	v_and_b32_e32 v159, 0xffff0000, v33
	v_lshlrev_b32_e32 v37, 16, v34
	v_and_b32_e32 v41, 0xffff0000, v34
	v_lshlrev_b32_e32 v39, 16, v35
	v_and_b32_e32 v43, 0xffff0000, v35
	v_pk_add_f32 v[32:33], v[56:57], v[56:57] op_sel:[0,1] op_sel_hi:[1,0]
	v_pk_add_f32 v[34:35], v[60:61], v[60:61] op_sel:[0,1] op_sel_hi:[1,0]
	v_pk_add_f32 v[62:63], v[74:75], v[72:73]
	v_pk_add_f32 v[110:111], v[70:71], v[68:69]
	v_mov_b32_e32 v33, v156
	v_mov_b32_e32 v35, v157
	v_pk_add_f32 v[32:33], v[32:33], v[34:35]
	v_pk_add_f32 v[34:35], v[62:63], v[62:63] op_sel:[0,1] op_sel_hi:[1,0]
	v_pk_add_f32 v[56:57], v[110:111], v[110:111] op_sel:[0,1] op_sel_hi:[1,0]
	v_lshlrev_b32_e32 v46, 16, v36
	v_and_b32_e32 v48, 0xffff0000, v36
	v_lshlrev_b32_e32 v152, 16, v38
	v_and_b32_e32 v153, 0xffff0000, v38
	v_mov_b32_e32 v35, v158
	v_mov_b32_e32 v57, v159
	v_add_f32_e32 v36, v46, v48
	v_add_f32_e32 v40, v50, v52
	v_add_f32_e32 v38, v152, v153
	v_add_f32_e32 v42, v154, v155
	v_pk_add_f32 v[34:35], v[34:35], v[56:57]
	v_pk_add_f32 v[56:57], v[38:39], v[42:43]
	v_pk_add_f32 v[32:33], v[32:33], v[34:35]
	v_pk_add_f32 v[34:35], v[36:37], v[40:41]
	s_waitcnt vmcnt(5)
	v_lshlrev_b32_e32 v40, 16, v21
	v_pk_add_f32 v[34:35], v[34:35], v[56:57]
	v_and_b32_e32 v42, 0xffff0000, v21
	v_pk_add_f32 v[32:33], v[32:33], v[34:35]
	v_and_b32_e32 v21, 64, v224
	v_pk_add_f32 v[110:111], v[32:33], v[32:33] op_sel:[0,1] op_sel_hi:[1,0]
	v_lshlrev_b32_e32 v57, 16, v30
	v_lshlrev_b32_e32 v56, 16, v28
	v_and_b32_e32 v33, 0xffff0000, v30
	v_and_b32_e32 v32, 0xffff0000, v28
	v_lshlrev_b32_e32 v63, 16, v31
	v_lshlrev_b32_e32 v62, 16, v29
	v_and_b32_e32 v61, 0xffff0000, v31
	v_and_b32_e32 v60, 0xffff0000, v29
	v_lshlrev_b32_e32 v36, 16, v20
	v_and_b32_e32 v38, 0xffff0000, v20
	v_xor_b32_e32 v20, 1, v224
	v_add_u32_e32 v21, 64, v21
	v_pk_add_f32 v[34:35], v[56:57], v[32:33]
	v_pk_add_f32 v[28:29], v[62:63], v[60:61]
	v_cmp_lt_i32_e32 vcc, v20, v21
	v_pk_add_f32 v[28:29], v[34:35], v[28:29]
	v_lshlrev_b32_e32 v35, 16, v25
	v_lshlrev_b32_e32 v34, 16, v24
	v_and_b32_e32 v31, 0xffff0000, v25
	v_and_b32_e32 v30, 0xffff0000, v24
	v_cndmask_b32_e32 v20, v224, v20, vcc
	v_pk_add_f32 v[24:25], v[34:35], v[30:31]
	v_lshlrev_b32_e32 v164, 2, v20
	v_xor_b32_e32 v20, 2, v224
	v_pk_add_f32 v[112:113], v[28:29], v[28:29] op_sel:[0,1] op_sel_hi:[1,0]
	v_pk_add_f32 v[122:123], v[24:25], v[24:25] op_sel:[0,1] op_sel_hi:[1,0]
	v_lshlrev_b32_e32 v29, 16, v27
	v_lshlrev_b32_e32 v28, 16, v26
	v_and_b32_e32 v25, 0xffff0000, v27
	v_and_b32_e32 v24, 0xffff0000, v26
	v_cmp_lt_i32_e32 vcc, v20, v21
	v_pk_add_f32 v[26:27], v[28:29], v[24:25]
	v_lshlrev_b32_e32 v160, 16, v22
	v_cndmask_b32_e32 v20, v224, v20, vcc
	v_pk_add_f32 v[26:27], v[26:27], v[26:27] op_sel:[0,1] op_sel_hi:[1,0]
	v_and_b32_e32 v161, 0xffff0000, v22
	v_lshlrev_b32_e32 v162, 16, v23
	v_and_b32_e32 v163, 0xffff0000, v23
	v_lshlrev_b32_e32 v165, 2, v20
	s_waitcnt vmcnt(4)
	v_and_b32_e32 v20, 0xffff0000, v19
	v_lshlrev_b32_e32 v21, 16, v19
	v_and_b32_e32 v22, 0xffff0000, v18
	v_lshlrev_b32_e32 v23, 16, v18
	v_and_b32_e32 v18, 0xffff0000, v17
	v_lshlrev_b32_e32 v19, 16, v17
	v_mov_b32_e32 v123, v19
	v_mov_b32_e32 v27, v18
	v_pk_add_f32 v[122:123], v[122:123], v[26:27]
	v_and_b32_e32 v26, 0xffff0000, v16
	v_lshlrev_b32_e32 v27, 16, v16
	v_add_f32_e32 v124, v36, v38
	v_add_f32_e32 v126, v40, v42
	v_add_f32_e32 v128, v160, v161
	v_add_f32_e32 v134, v162, v163
	v_mov_b32_e32 v129, v21
	v_mov_b32_e32 v135, v20
	v_mov_b32_e32 v125, v23
	v_mov_b32_e32 v127, v22
	v_mov_b32_e32 v111, v27
	v_mov_b32_e32 v113, v26
	v_pk_add_f32 v[128:129], v[128:129], v[134:135]
	v_pk_add_f32 v[124:125], v[124:125], v[126:127]
	v_pk_add_f32 v[16:17], v[110:111], v[112:113]
	v_pk_add_f32 v[124:125], v[124:125], v[128:129]
	v_pk_add_f32 v[16:17], v[16:17], v[122:123]
	s_nop 0
	v_pk_add_f32 v[16:17], v[16:17], v[124:125]
	s_nop 0
	v_add_f32_e32 v16, v16, v17
	ds_bpermute_b32 v17, v164, v16
	s_waitcnt lgkmcnt(0)
	v_add_f32_e32 v16, v16, v17
	ds_bpermute_b32 v17, v165, v16
	s_waitcnt lgkmcnt(0)
	v_add_f32_e32 v17, v16, v17
	v_fmac_f32_e32 v114, 0xbb000000, v17
	v_mul_f32_e32 v110, v114, v114
	v_fmac_f32_e32 v116, 0xbb000000, v17
	v_fmac_f32_e32 v110, v116, v116
	v_fmac_f32_e32 v118, 0xbb000000, v17
	v_fmac_f32_e32 v110, v118, v118
	v_fmac_f32_e32 v120, 0xbb000000, v17
	v_fmac_f32_e32 v110, v120, v120
	v_fmac_f32_e32 v115, 0xbb000000, v17
	v_fmac_f32_e32 v110, v115, v115
	v_fmac_f32_e32 v117, 0xbb000000, v17
	v_fmac_f32_e32 v110, v117, v117
	v_fmac_f32_e32 v119, 0xbb000000, v17
	v_fmac_f32_e32 v110, v119, v119
	v_fmac_f32_e32 v121, 0xbb000000, v17
	v_fmac_f32_e32 v110, v121, v121
	v_fmac_f32_e32 v108, 0xbb000000, v17
	v_fmac_f32_e32 v110, v108, v108
	v_fmac_f32_e32 v106, 0xbb000000, v17
	v_fmac_f32_e32 v110, v106, v106
	v_fmac_f32_e32 v109, 0xbb000000, v17
	v_fmac_f32_e32 v110, v109, v109
	v_fmac_f32_e32 v107, 0xbb000000, v17
	v_fmac_f32_e32 v110, v107, v107
	v_fmac_f32_e32 v104, 0xbb000000, v17
	v_fmac_f32_e32 v110, v104, v104
	v_fmac_f32_e32 v102, 0xbb000000, v17
	v_fmac_f32_e32 v110, v102, v102
	v_fmac_f32_e32 v105, 0xbb000000, v17
	v_fmac_f32_e32 v110, v105, v105
	v_fmac_f32_e32 v103, 0xbb000000, v17
	v_fmac_f32_e32 v110, v103, v103
	v_fmac_f32_e32 v131, 0xbb000000, v17
	v_fmac_f32_e32 v110, v131, v131
	v_fmac_f32_e32 v133, 0xbb000000, v17
	v_fmac_f32_e32 v110, v133, v133
	v_fmac_f32_e32 v136, 0xbb000000, v17
	v_fmac_f32_e32 v110, v136, v136
	v_fmac_f32_e32 v137, 0xbb000000, v17
	v_fmac_f32_e32 v110, v137, v137
	v_fmac_f32_e32 v138, 0xbb000000, v17
	v_fmac_f32_e32 v110, v138, v138
	v_fmac_f32_e32 v139, 0xbb000000, v17
	v_fmac_f32_e32 v110, v139, v139
	v_fmac_f32_e32 v140, 0xbb000000, v17
	v_fmac_f32_e32 v110, v140, v140
	v_fmac_f32_e32 v141, 0xbb000000, v17
	v_fmac_f32_e32 v110, v141, v141
	v_fmac_f32_e32 v142, 0xbb000000, v17
	v_fmac_f32_e32 v110, v142, v142
	v_fmac_f32_e32 v101, 0xbb000000, v17
	v_fmac_f32_e32 v110, v101, v101
	v_fmac_f32_e32 v143, 0xbb000000, v17
	v_fmac_f32_e32 v110, v143, v143
	v_fmac_f32_e32 v144, 0xbb000000, v17
	v_fmac_f32_e32 v110, v144, v144
	v_fmac_f32_e32 v55, 0xbb000000, v17
	v_fmac_f32_e32 v110, v55, v55
	v_fmac_f32_e32 v59, 0xbb000000, v17
	v_fmac_f32_e32 v110, v59, v59
	v_fmac_f32_e32 v65, 0xbb000000, v17
	v_fmac_f32_e32 v110, v65, v65
	v_fmac_f32_e32 v67, 0xbb000000, v17
	v_fmac_f32_e32 v110, v67, v67
	v_fmac_f32_e32 v94, 0xbb000000, v17
	v_fmac_f32_e32 v110, v94, v94
	v_fmac_f32_e32 v92, 0xbb000000, v17
	v_fmac_f32_e32 v110, v92, v92
	v_fmac_f32_e32 v98, 0xbb000000, v17
	v_fmac_f32_e32 v110, v98, v98
	v_fmac_f32_e32 v96, 0xbb000000, v17
	v_fmac_f32_e32 v110, v96, v96
	v_fmac_f32_e32 v95, 0xbb000000, v17
	v_fmac_f32_e32 v110, v95, v95
	v_fmac_f32_e32 v93, 0xbb000000, v17
	v_fmac_f32_e32 v110, v93, v93
	v_fmac_f32_e32 v99, 0xbb000000, v17
	v_fmac_f32_e32 v110, v99, v99
	v_fmac_f32_e32 v97, 0xbb000000, v17
	v_fmac_f32_e32 v110, v97, v97
	v_fmac_f32_e32 v90, 0xbb000000, v17
	v_fmac_f32_e32 v110, v90, v90
	v_fmac_f32_e32 v88, 0xbb000000, v17
	v_fmac_f32_e32 v110, v88, v88
	v_fmac_f32_e32 v91, 0xbb000000, v17
	v_fmac_f32_e32 v110, v91, v91
	v_fmac_f32_e32 v89, 0xbb000000, v17
	v_fmac_f32_e32 v110, v89, v89
	v_fmac_f32_e32 v86, 0xbb000000, v17
	v_fmac_f32_e32 v110, v86, v86
	v_fmac_f32_e32 v84, 0xbb000000, v17
	v_fmac_f32_e32 v110, v84, v84
	v_fmac_f32_e32 v87, 0xbb000000, v17
	v_fmac_f32_e32 v110, v87, v87
	v_fmac_f32_e32 v85, 0xbb000000, v17
	v_fmac_f32_e32 v110, v85, v85
	v_fmac_f32_e32 v54, 0xbb000000, v17
	v_fmac_f32_e32 v110, v54, v54
	v_fmac_f32_e32 v58, 0xbb000000, v17
	v_fmac_f32_e32 v110, v58, v58
	v_fmac_f32_e32 v64, 0xbb000000, v17
	v_fmac_f32_e32 v110, v64, v64
	v_fmac_f32_e32 v66, 0xbb000000, v17
	v_fmac_f32_e32 v110, v66, v66
	v_fmac_f32_e32 v100, 0xbb000000, v17
	v_fmac_f32_e32 v110, v100, v100
	v_fmac_f32_e32 v145, 0xbb000000, v17
	v_fmac_f32_e32 v110, v145, v145
	v_fmac_f32_e32 v146, 0xbb000000, v17
	v_fmac_f32_e32 v110, v146, v146
	v_fmac_f32_e32 v147, 0xbb000000, v17
	v_fmac_f32_e32 v110, v147, v147
	v_fmac_f32_e32 v148, 0xbb000000, v17
	v_fmac_f32_e32 v110, v148, v148
	v_fmac_f32_e32 v149, 0xbb000000, v17
	v_fmac_f32_e32 v110, v149, v149
	v_fmac_f32_e32 v150, 0xbb000000, v17
	v_fmac_f32_e32 v110, v150, v150
	v_fmac_f32_e32 v151, 0xbb000000, v17
	v_fmac_f32_e32 v110, v151, v151
	v_fmac_f32_e32 v47, 0xbb000000, v17
	v_fmac_f32_e32 v110, v47, v47
	v_fmac_f32_e32 v49, 0xbb000000, v17
	v_fmac_f32_e32 v110, v49, v49
	v_fmac_f32_e32 v51, 0xbb000000, v17
	v_fmac_f32_e32 v110, v51, v51
	v_fmac_f32_e32 v53, 0xbb000000, v17
	v_fmac_f32_e32 v110, v53, v53
	v_fmac_f32_e32 v78, 0xbb000000, v17
	v_fmac_f32_e32 v110, v78, v78
	v_fmac_f32_e32 v76, 0xbb000000, v17
	v_fmac_f32_e32 v110, v76, v76
	v_fmac_f32_e32 v82, 0xbb000000, v17
	v_fmac_f32_e32 v110, v82, v82
	v_fmac_f32_e32 v80, 0xbb000000, v17
	v_fmac_f32_e32 v110, v80, v80
	v_fmac_f32_e32 v79, 0xbb000000, v17
	v_fmac_f32_e32 v110, v79, v79
	v_fmac_f32_e32 v77, 0xbb000000, v17
	v_fmac_f32_e32 v110, v77, v77
	v_fmac_f32_e32 v83, 0xbb000000, v17
	v_fmac_f32_e32 v110, v83, v83
	v_fmac_f32_e32 v81, 0xbb000000, v17
	v_fmac_f32_e32 v110, v81, v81
	v_fmac_f32_e32 v74, 0xbb000000, v17
	v_fmac_f32_e32 v110, v74, v74
	v_fmac_f32_e32 v72, 0xbb000000, v17
	v_fmac_f32_e32 v110, v72, v72
	v_fmac_f32_e32 v75, 0xbb000000, v17
	v_fmac_f32_e32 v110, v75, v75
	v_fmac_f32_e32 v73, 0xbb000000, v17
	v_fmac_f32_e32 v110, v73, v73
	v_fmac_f32_e32 v70, 0xbb000000, v17
	v_fmac_f32_e32 v110, v70, v70
	v_fmac_f32_e32 v68, 0xbb000000, v17
	v_fmac_f32_e32 v110, v68, v68
	v_fmac_f32_e32 v71, 0xbb000000, v17
	v_fmac_f32_e32 v110, v71, v71
	v_fmac_f32_e32 v69, 0xbb000000, v17
	v_fmac_f32_e32 v110, v69, v69
	v_fmac_f32_e32 v46, 0xbb000000, v17
	v_fmac_f32_e32 v110, v46, v46
	v_fmac_f32_e32 v48, 0xbb000000, v17
	v_fmac_f32_e32 v110, v48, v48
	v_fmac_f32_e32 v50, 0xbb000000, v17
	v_fmac_f32_e32 v110, v50, v50
	v_fmac_f32_e32 v52, 0xbb000000, v17
	v_fmac_f32_e32 v110, v52, v52
	v_fmac_f32_e32 v152, 0xbb000000, v17
	v_fmac_f32_e32 v110, v152, v152
	v_fmac_f32_e32 v153, 0xbb000000, v17
	v_fmac_f32_e32 v110, v153, v153
	v_fmac_f32_e32 v154, 0xbb000000, v17
	v_fmac_f32_e32 v110, v154, v154
	v_fmac_f32_e32 v155, 0xbb000000, v17
	v_fmac_f32_e32 v110, v155, v155
	v_fmac_f32_e32 v156, 0xbb000000, v17
	v_fmac_f32_e32 v110, v156, v156
	v_fmac_f32_e32 v157, 0xbb000000, v17
	v_fmac_f32_e32 v110, v157, v157
	v_fmac_f32_e32 v158, 0xbb000000, v17
	v_fmac_f32_e32 v110, v158, v158
	v_fmac_f32_e32 v159, 0xbb000000, v17
	v_fmac_f32_e32 v110, v159, v159
	v_fmac_f32_e32 v37, 0xbb000000, v17
	v_fmac_f32_e32 v110, v37, v37
	v_fmac_f32_e32 v41, 0xbb000000, v17
	v_fmac_f32_e32 v110, v41, v41
	v_fmac_f32_e32 v39, 0xbb000000, v17
	v_fmac_f32_e32 v110, v39, v39
	v_fmac_f32_e32 v43, 0xbb000000, v17
	v_fmac_f32_e32 v110, v43, v43
	v_fmac_f32_e32 v56, 0xbb000000, v17
	v_fmac_f32_e32 v110, v56, v56
	v_fmac_f32_e32 v32, 0xbb000000, v17
	v_fmac_f32_e32 v110, v32, v32
	v_fmac_f32_e32 v62, 0xbb000000, v17
	v_fmac_f32_e32 v110, v62, v62
	v_fmac_f32_e32 v60, 0xbb000000, v17
	v_fmac_f32_e32 v110, v60, v60
	v_fmac_f32_e32 v57, 0xbb000000, v17
	v_fmac_f32_e32 v110, v57, v57
	v_fmac_f32_e32 v33, 0xbb000000, v17
	v_fmac_f32_e32 v110, v33, v33
	v_fmac_f32_e32 v63, 0xbb000000, v17
	v_fmac_f32_e32 v110, v63, v63
	v_fmac_f32_e32 v61, 0xbb000000, v17
	v_fmac_f32_e32 v110, v61, v61
	v_fmac_f32_e32 v34, 0xbb000000, v17
	v_fmac_f32_e32 v110, v34, v34
	v_fmac_f32_e32 v30, 0xbb000000, v17
	v_fmac_f32_e32 v110, v30, v30
	v_fmac_f32_e32 v35, 0xbb000000, v17
	v_fmac_f32_e32 v110, v35, v35
	v_fmac_f32_e32 v31, 0xbb000000, v17
	v_fmac_f32_e32 v110, v31, v31
	v_fmac_f32_e32 v28, 0xbb000000, v17
	v_fmac_f32_e32 v110, v28, v28
	v_fmac_f32_e32 v24, 0xbb000000, v17
	v_fmac_f32_e32 v110, v24, v24
	v_fmac_f32_e32 v29, 0xbb000000, v17
	v_fmac_f32_e32 v110, v29, v29
	v_fmac_f32_e32 v25, 0xbb000000, v17
	v_fmac_f32_e32 v110, v25, v25
	v_fmac_f32_e32 v36, 0xbb000000, v17
	v_fmac_f32_e32 v110, v36, v36
	v_fmac_f32_e32 v38, 0xbb000000, v17
	v_fmac_f32_e32 v110, v38, v38
	v_fmac_f32_e32 v40, 0xbb000000, v17
	v_fmac_f32_e32 v110, v40, v40
	v_fmac_f32_e32 v42, 0xbb000000, v17
	v_fmac_f32_e32 v110, v42, v42
	v_fmac_f32_e32 v160, 0xbb000000, v17
	v_fmac_f32_e32 v110, v160, v160
	v_fmac_f32_e32 v161, 0xbb000000, v17
	v_mul_f32_e32 v16, 0x3b000000, v17
	v_fmac_f32_e32 v110, v161, v161
	v_fmac_f32_e32 v162, 0xbb000000, v17
	v_fmac_f32_e32 v110, v162, v162
	v_fmac_f32_e32 v163, 0xbb000000, v17
	v_pk_add_f32 v[24:25], v[26:27], v[16:17] op_sel_hi:[1,0] neg_lo:[0,1] neg_hi:[0,1]
	v_fmac_f32_e32 v110, v163, v163
	v_pk_mul_f32 v[24:25], v[24:25], v[24:25]
	v_pk_add_f32 v[18:19], v[18:19], v[16:17] op_sel_hi:[1,0] neg_lo:[0,1] neg_hi:[0,1]
	v_add_f32_e32 v25, v25, v110
	v_add_f32_e32 v24, v24, v25
	v_pk_mul_f32 v[18:19], v[18:19], v[18:19]
	v_lshlrev_b32_e32 v35, 2, v45
	v_add_f32_e32 v19, v19, v24
	v_add_f32_e32 v24, v18, v19
	v_pk_add_f32 v[18:19], v[22:23], v[16:17] op_sel_hi:[1,0] neg_lo:[0,1] neg_hi:[0,1]
	s_waitcnt vmcnt(3)
	v_lshlrev_b32_e32 v36, 16, v12
	v_pk_mul_f32 v[18:19], v[18:19], v[18:19]
	v_and_b32_e32 v12, 0xffff0000, v12
	v_add_f32_e32 v19, v19, v24
	v_add_f32_e32 v22, v18, v19
	v_pk_add_f32 v[18:19], v[20:21], v[16:17] op_sel_hi:[1,0] neg_lo:[0,1] neg_hi:[0,1]
	v_fmac_f32_e32 v36, 0xbb000000, v17
	v_pk_mul_f32 v[18:19], v[18:19], v[18:19]
	v_fmac_f32_e32 v12, 0xbb000000, v17
	v_add_f32_e32 v16, v19, v22
	v_add_f32_e32 v16, v18, v16
	ds_bpermute_b32 v18, v164, v16
	v_lshlrev_b32_e32 v34, 1, v44
	v_lshlrev_b32_e32 v37, 16, v13
	v_fmac_f32_e32 v37, 0xbb000000, v17
	v_and_b32_e32 v13, 0xffff0000, v13
	s_waitcnt lgkmcnt(0)
	v_add_f32_e32 v16, v16, v18
	ds_bpermute_b32 v18, v165, v16
	v_fmac_f32_e32 v13, 0xbb000000, v17
	v_lshlrev_b32_e32 v38, 16, v14
	v_fmac_f32_e32 v38, 0xbb000000, v17
	v_and_b32_e32 v14, 0xffff0000, v14
	s_waitcnt lgkmcnt(0)
	v_add_f32_e32 v16, v16, v18
	v_fmamk_f32 v16, v16, 0x3b000000, v220
	v_cmp_gt_f32_e32 vcc, s13, v16
	v_mul_f32_e32 v18, 0x4b800000, v16
	v_fmac_f32_e32 v14, 0xbb000000, v17
	v_cndmask_b32_e32 v16, v16, v18, vcc
	v_rsq_f32_e32 v16, v16
	v_lshlrev_b32_e32 v39, 16, v15
	v_fmac_f32_e32 v39, 0xbb000000, v17
	v_and_b32_e32 v15, 0xffff0000, v15
	v_mul_f32_e32 v18, 0x45800000, v16
	v_cndmask_b32_e32 v16, v16, v18, vcc
	global_load_dwordx4 v[18:21], v35, s[40:41] offset:16
	global_load_dwordx4 v[22:25], v35, s[40:41]
	global_load_dwordx4 v[26:29], v35, s[46:47] offset:16
	global_load_dwordx4 v[30:33], v35, s[46:47]
	v_mul_f32_e32 v36, v36, v16
	v_mul_f32_e32 v12, v12, v16
	v_fmac_f32_e32 v15, 0xbb000000, v17
	v_or_b32_e32 v131, s36, v132
	v_or_b32_e32 v142, 16, v131
	v_or_b32_e32 v141, 32, v131
	v_or_b32_e32 v140, 48, v131
	v_or_b32_e32 v139, 64, v131
	v_or_b32_e32 v138, 0x50, v131
	v_or_b32_e32 v137, 0x60, v131
	v_or_b32_e32 v133, 0x70, v131
	s_waitcnt vmcnt(0)
	v_fma_f32 v22, v22, v36, v30
	v_mul_u32_u24_e32 v30, 0x110, v45
	v_fma_f32 v12, v23, v12, v31
	v_add3_u32 v30, 0, v34, v30
	v_cvt_pk_bf16_f32 v12, v12, s0
	ds_write_b16 v30, v12 offset:272
	v_mul_f32_e32 v12, v37, v16
	v_fma_f32 v12, v24, v12, v32
	v_cvt_pk_bf16_f32 v12, v12, s0
	ds_write_b16 v30, v12 offset:544
	v_mul_f32_e32 v12, v13, v16
	v_fmac_f32_e32 v33, v25, v12
	v_cvt_pk_bf16_f32 v12, v33, s0
	ds_write_b16 v30, v12 offset:816
	v_mul_f32_e32 v12, v38, v16
	v_fma_f32 v12, v18, v12, v26
	v_cvt_pk_bf16_f32 v12, v12, s0
	ds_write_b16 v30, v12 offset:1088
	v_mul_f32_e32 v12, v14, v16
	v_fma_f32 v12, v19, v12, v27
	v_cvt_pk_bf16_f32 v12, v12, s0
	ds_write_b16 v30, v12 offset:1360
	v_mul_f32_e32 v12, v39, v16
	v_fma_f32 v12, v20, v12, v28
	v_cvt_pk_bf16_f32 v12, v12, s0
	ds_write_b16 v30, v12 offset:1632
	v_mul_f32_e32 v12, v15, v16
	v_fmac_f32_e32 v29, v21, v12
	v_cvt_pk_bf16_f32 v22, v22, s0
	v_cvt_pk_bf16_f32 v12, v29, s0
	ds_write_b16 v30, v22
	ds_write_b16 v30, v12 offset:1904
	global_load_dwordx4 v[12:15], v35, s[40:41] offset:144
	global_load_dwordx4 v[18:21], v35, s[40:41] offset:128
	global_load_dwordx4 v[22:25], v35, s[46:47] offset:144
	global_load_dwordx4 v[26:29], v35, s[46:47] offset:128
	v_lshlrev_b32_e32 v31, 16, v8
	v_and_b32_e32 v8, 0xffff0000, v8
	v_fmac_f32_e32 v8, 0xbb000000, v17
	v_mul_f32_e32 v8, v8, v16
	v_lshlrev_b32_e32 v32, 16, v9
	v_fmac_f32_e32 v32, 0xbb000000, v17
	v_and_b32_e32 v9, 0xffff0000, v9
	v_fmac_f32_e32 v9, 0xbb000000, v17
	v_lshlrev_b32_e32 v33, 16, v10
	v_fmac_f32_e32 v33, 0xbb000000, v17
	v_and_b32_e32 v10, 0xffff0000, v10
	v_fmac_f32_e32 v10, 0xbb000000, v17
	v_lshlrev_b32_e32 v34, 16, v11
	v_fmac_f32_e32 v34, 0xbb000000, v17
	v_and_b32_e32 v11, 0xffff0000, v11
	v_fmac_f32_e32 v31, 0xbb000000, v17
	v_fmac_f32_e32 v11, 0xbb000000, v17
	v_mul_f32_e32 v31, v31, v16
	s_waitcnt vmcnt(0)
	v_fma_f32 v8, v19, v8, v27
	v_cvt_pk_bf16_f32 v8, v8, s0
	ds_write_b16 v30, v8 offset:8976
	v_mul_f32_e32 v8, v32, v16
	v_fma_f32 v8, v20, v8, v28
	v_cvt_pk_bf16_f32 v8, v8, s0
	ds_write_b16 v30, v8 offset:9248
	v_mul_f32_e32 v8, v9, v16
	v_fmac_f32_e32 v29, v21, v8
	v_cvt_pk_bf16_f32 v8, v29, s0
	ds_write_b16 v30, v8 offset:9520
	v_mul_f32_e32 v8, v33, v16
	v_fma_f32 v8, v12, v8, v22
	v_cvt_pk_bf16_f32 v8, v8, s0
	ds_write_b16 v30, v8 offset:9792
	v_mul_f32_e32 v8, v10, v16
	v_fma_f32 v8, v13, v8, v23
	v_cvt_pk_bf16_f32 v8, v8, s0
	ds_write_b16 v30, v8 offset:10064
	v_mul_f32_e32 v8, v34, v16
	v_fma_f32 v8, v14, v8, v24
	v_cvt_pk_bf16_f32 v8, v8, s0
	ds_write_b16 v30, v8 offset:10336
	v_mul_f32_e32 v8, v11, v16
	v_fma_f32 v18, v18, v31, v26
	v_fmac_f32_e32 v25, v15, v8
	v_cvt_pk_bf16_f32 v18, v18, s0
	v_cvt_pk_bf16_f32 v8, v25, s0
	ds_write_b16 v30, v18 offset:8704
	ds_write_b16 v30, v8 offset:10608
	global_load_dwordx4 v[8:11], v35, s[40:41] offset:272
	global_load_dwordx4 v[12:15], v35, s[40:41] offset:256
	global_load_dwordx4 v[18:21], v35, s[46:47] offset:272
	global_load_dwordx4 v[22:25], v35, s[46:47] offset:256
	v_lshlrev_b32_e32 v26, 16, v4
	v_and_b32_e32 v4, 0xffff0000, v4
	v_fmac_f32_e32 v4, 0xbb000000, v17
	v_mul_f32_e32 v4, v4, v16
	v_lshlrev_b32_e32 v27, 16, v5
	v_fmac_f32_e32 v27, 0xbb000000, v17
	v_and_b32_e32 v5, 0xffff0000, v5
	v_fmac_f32_e32 v5, 0xbb000000, v17
	v_lshlrev_b32_e32 v28, 16, v6
	v_fmac_f32_e32 v28, 0xbb000000, v17
	v_and_b32_e32 v6, 0xffff0000, v6
	v_fmac_f32_e32 v6, 0xbb000000, v17
	v_lshlrev_b32_e32 v29, 16, v7
	v_fmac_f32_e32 v29, 0xbb000000, v17
	v_and_b32_e32 v7, 0xffff0000, v7
	v_fmac_f32_e32 v26, 0xbb000000, v17
	v_fmac_f32_e32 v7, 0xbb000000, v17
	v_mul_f32_e32 v26, v26, v16
	s_waitcnt vmcnt(0)
	v_fma_f32 v4, v13, v4, v23
	v_cvt_pk_bf16_f32 v4, v4, s0
	ds_write_b16 v30, v4 offset:17680
	v_mul_f32_e32 v4, v27, v16
	v_fma_f32 v4, v14, v4, v24
	v_cvt_pk_bf16_f32 v4, v4, s0
	ds_write_b16 v30, v4 offset:17952
	v_mul_f32_e32 v4, v5, v16
	v_fmac_f32_e32 v25, v15, v4
	v_cvt_pk_bf16_f32 v4, v25, s0
	ds_write_b16 v30, v4 offset:18224
	v_mul_f32_e32 v4, v28, v16
	v_fma_f32 v4, v8, v4, v18
	v_cvt_pk_bf16_f32 v4, v4, s0
	ds_write_b16 v30, v4 offset:18496
	v_mul_f32_e32 v4, v6, v16
	v_fma_f32 v4, v9, v4, v19
	v_cvt_pk_bf16_f32 v4, v4, s0
	ds_write_b16 v30, v4 offset:18768
	v_mul_f32_e32 v4, v29, v16
	v_fma_f32 v4, v10, v4, v20
	v_cvt_pk_bf16_f32 v4, v4, s0
	ds_write_b16 v30, v4 offset:19040
	v_mul_f32_e32 v4, v7, v16
	v_fma_f32 v12, v12, v26, v22
	v_fmac_f32_e32 v21, v11, v4
	v_cvt_pk_bf16_f32 v12, v12, s0
	v_cvt_pk_bf16_f32 v4, v21, s0
	ds_write_b16 v30, v12 offset:17408
	ds_write_b16 v30, v4 offset:19312
	global_load_dwordx4 v[4:7], v35, s[40:41] offset:400
	global_load_dwordx4 v[8:11], v35, s[40:41] offset:384
	global_load_dwordx4 v[12:15], v35, s[46:47] offset:400
	global_load_dwordx4 v[18:21], v35, s[46:47] offset:384
	v_lshlrev_b32_e32 v22, 16, v0
	v_and_b32_e32 v0, 0xffff0000, v0
	v_fmac_f32_e32 v0, 0xbb000000, v17
	v_mul_f32_e32 v0, v0, v16
	v_lshlrev_b32_e32 v23, 16, v1
	v_fmac_f32_e32 v23, 0xbb000000, v17
	v_and_b32_e32 v1, 0xffff0000, v1
	v_fmac_f32_e32 v1, 0xbb000000, v17
	v_lshlrev_b32_e32 v24, 16, v2
	v_fmac_f32_e32 v24, 0xbb000000, v17
	v_and_b32_e32 v2, 0xffff0000, v2
	v_fmac_f32_e32 v2, 0xbb000000, v17
	v_lshlrev_b32_e32 v25, 16, v3
	v_fmac_f32_e32 v25, 0xbb000000, v17
	v_and_b32_e32 v3, 0xffff0000, v3
	v_fmac_f32_e32 v3, 0xbb000000, v17
	v_fmac_f32_e32 v22, 0xbb000000, v17
	v_mul_f32_e32 v22, v22, v16
	v_and_b32_e32 v17, -16, v130
	s_waitcnt vmcnt(0)
	v_fma_f32 v0, v9, v0, v19
	v_cvt_pk_bf16_f32 v0, v0, s0
	ds_write_b16 v30, v0 offset:26384
	v_mul_f32_e32 v0, v23, v16
	v_fma_f32 v0, v10, v0, v20
	v_cvt_pk_bf16_f32 v0, v0, s0
	ds_write_b16 v30, v0 offset:26656
	v_mul_f32_e32 v0, v1, v16
	v_fmac_f32_e32 v21, v11, v0
	v_cvt_pk_bf16_f32 v0, v21, s0
	ds_write_b16 v30, v0 offset:26928
	v_mul_f32_e32 v0, v24, v16
	v_fma_f32 v0, v4, v0, v12
	v_cvt_pk_bf16_f32 v0, v0, s0
	ds_write_b16 v30, v0 offset:27200
	v_mul_f32_e32 v0, v2, v16
	v_fma_f32 v0, v5, v0, v13
	v_cvt_pk_bf16_f32 v0, v0, s0
	ds_write_b16 v30, v0 offset:27472
	v_mul_f32_e32 v0, v25, v16
	v_fma_f32 v0, v6, v0, v14
	v_cvt_pk_bf16_f32 v0, v0, s0
	ds_write_b16 v30, v0 offset:27744
	v_mul_f32_e32 v0, v3, v16
	v_ashrrev_i32_e32 v4, 4, v130
	v_fmac_f32_e32 v15, v7, v0
	v_lshlrev_b32_e32 v92, 2, v4
	v_cvt_pk_bf16_f32 v0, v15, s0
	v_ashrrev_i32_e32 v93, 31, v92
	ds_write_b16 v30, v0 offset:28016
	v_lshl_add_u64 v[0:1], v[92:93], 1, s[8:9]
	v_mad_u64_u32 v[2:3], s[8:9], v131, s14, v[0:1]
	v_mad_i32_i24 v3, s37, v225, v3
	global_load_dwordx2 v[126:127], v[2:3], off offset:1024
	v_add_co_u32_e32 v2, vcc, s15, v2
	v_fma_f32 v8, v8, v22, v18
	s_nop 0
	v_addc_co_u32_e32 v3, vcc, 0, v3, vcc
	global_load_dwordx2 v[128:129], v[2:3], off offset:2048
	v_mad_u64_u32 v[2:3], s[8:9], v142, s14, v[0:1]
	v_mad_i32_i24 v3, s37, v225, v3
	global_load_dwordx2 v[122:123], v[2:3], off offset:1024
	v_add_co_u32_e32 v2, vcc, s15, v2
	v_cvt_pk_bf16_f32 v8, v8, s0
	s_nop 0
	v_addc_co_u32_e32 v3, vcc, 0, v3, vcc
	global_load_dwordx2 v[124:125], v[2:3], off offset:2048
	v_mad_u64_u32 v[2:3], s[8:9], v141, s14, v[0:1]
	v_mad_i32_i24 v3, s37, v225, v3
	global_load_dwordx2 v[118:119], v[2:3], off offset:1024
	v_add_co_u32_e32 v2, vcc, s15, v2
	ds_write_b16 v30, v8 offset:26112
	s_nop 0
	v_addc_co_u32_e32 v3, vcc, 0, v3, vcc
	global_load_dwordx2 v[120:121], v[2:3], off offset:2048
	v_mad_u64_u32 v[2:3], s[8:9], v140, s14, v[0:1]
	v_mad_i32_i24 v3, s37, v225, v3
	global_load_dwordx2 v[114:115], v[2:3], off offset:1024
	v_add_co_u32_e32 v2, vcc, s15, v2
	v_or_b32_e32 v16, s10, v132
	s_nop 0
	v_addc_co_u32_e32 v3, vcc, 0, v3, vcc
	global_load_dwordx2 v[116:117], v[2:3], off offset:2048
	v_mad_u64_u32 v[2:3], s[8:9], v139, s14, v[0:1]
	v_mad_i32_i24 v3, s37, v225, v3
	global_load_dwordx2 v[110:111], v[2:3], off offset:1024
	v_add_co_u32_e32 v2, vcc, s15, v2
	v_or_b32_e32 v132, s60, v132
	s_nop 0
	v_addc_co_u32_e32 v3, vcc, 0, v3, vcc
	global_load_dwordx2 v[112:113], v[2:3], off offset:2048
	v_mad_u64_u32 v[2:3], s[8:9], v138, s14, v[0:1]
	v_mad_i32_i24 v3, s37, v225, v3
	global_load_dwordx2 v[106:107], v[2:3], off offset:1024
	v_add_co_u32_e32 v2, vcc, s15, v2
	v_lshlrev_b32_e32 v136, 2, v132
	s_nop 0
	v_addc_co_u32_e32 v3, vcc, 0, v3, vcc
	global_load_dwordx2 v[108:109], v[2:3], off offset:2048
	v_mad_u64_u32 v[2:3], s[8:9], v137, s14, v[0:1]
	v_mad_u64_u32 v[0:1], s[8:9], v133, s14, v[0:1]
	v_mad_i32_i24 v3, s37, v225, v3
	v_mad_i32_i24 v1, s37, v225, v1
	global_load_dwordx2 v[100:101], v[2:3], off offset:1024
	global_load_dwordx2 v[96:97], v[0:1], off offset:1024
	v_add_co_u32_e32 v2, vcc, s15, v2
	s_add_u32 s8, s3, s7
	s_nop 0
	v_addc_co_u32_e32 v3, vcc, 0, v3, vcc
	v_add_co_u32_e32 v0, vcc, s15, v0
	s_addc_u32 s9, s11, 0
	s_nop 0
	v_addc_co_u32_e32 v1, vcc, 0, v1, vcc
	global_load_dwordx2 v[98:99], v[0:1], off offset:2048
	v_lshlrev_b32_e32 v0, 3, v4
	v_ashrrev_i32_e32 v1, 31, v0
	v_lshl_add_u64 v[0:1], v[0:1], 1, s[8:9]
	v_lshl_add_u64 v[0:1], v[0:1], 0, v[194:195]
	global_load_dwordx2 v[104:105], v[2:3], off offset:2048
	global_load_dwordx4 v[144:147], v[0:1], off
	v_add_co_u32_e32 v2, vcc, s4, v0
	s_movk_i32 s7, 0x4000
	s_nop 0
	v_addc_co_u32_e32 v3, vcc, 0, v1, vcc
	global_load_dwordx4 v[88:91], v[2:3], off offset:-4096
	global_load_dwordx4 v[80:83], v[2:3], off
	global_load_dwordx4 v[84:87], v[2:3], off offset:64
	v_add_co_u32_e32 v2, vcc, s35, v0
	s_waitcnt vmcnt(18)
	v_lshlrev_b32_e32 v143, 16, v128
	v_addc_co_u32_e32 v3, vcc, 0, v1, vcc
	v_add_co_u32_e32 v4, vcc, s7, v0
	s_movk_i32 s7, 0x5000
	s_nop 0
	v_addc_co_u32_e32 v5, vcc, 0, v1, vcc
	global_load_dwordx4 v[72:75], v[4:5], off offset:-4096
	global_load_dwordx4 v[76:79], v[2:3], off offset:64
	global_load_dwordx4 v[60:63], v[4:5], off
	global_load_dwordx4 v[64:67], v[4:5], off offset:64
	global_load_dwordx4 v[68:71], v[4:5], off offset:128
	v_add_co_u32_e32 v2, vcc, s7, v0
	s_movk_i32 s7, 0x7000
	s_nop 0
	v_addc_co_u32_e32 v3, vcc, 0, v1, vcc
	v_add_co_u32_e32 v4, vcc, s95, v0
	v_and_b32_e32 v128, 0xffff0000, v128
	s_nop 0
	v_addc_co_u32_e32 v5, vcc, 0, v1, vcc
	v_add_co_u32_e32 v12, vcc, s7, v0
	s_movk_i32 s7, 0x110
	v_mul_lo_u32 v16, v16, s7
	v_addc_co_u32_e32 v13, vcc, 0, v1, vcc
	v_add3_u32 v28, 0, v16, v17
	global_load_dwordx4 v[48:51], v[4:5], off offset:-4096
	global_load_dwordx4 v[52:55], v[2:3], off offset:64
	global_load_dwordx4 v[56:59], v[2:3], off offset:128
	global_load_dwordx4 v[32:35], v[4:5], off
	global_load_dwordx4 v[36:39], v[4:5], off offset:64
	global_load_dwordx4 v[40:43], v[4:5], off offset:128
	global_load_dwordx4 v[44:47], v[4:5], off offset:192
	s_nop 0
	global_load_dwordx4 v[0:3], v[12:13], off
	global_load_dwordx4 v[4:7], v[12:13], off offset:64
	global_load_dwordx4 v[8:11], v[12:13], off offset:128
	s_nop 0
	global_load_dwordx4 v[12:15], v[12:13], off offset:192
	s_waitcnt lgkmcnt(0)
	s_barrier
	ds_read_b128 v[16:19], v28
	ds_read_b128 v[20:23], v28 offset:64
	ds_read_b128 v[24:27], v28 offset:128
	ds_read_b128 v[28:31], v28 offset:192
	global_load_dword v132, v136, s[0:1]
	global_load_dword v160, v136, s[0:1] offset:64
	global_load_dword v162, v136, s[0:1] offset:128
	global_load_dword v164, v136, s[0:1] offset:192
	global_load_dword v166, v136, s[0:1] offset:256
	global_load_dword v168, v136, s[0:1] offset:320
	global_load_dword v170, v136, s[0:1] offset:384
	global_load_dword v172, v136, s[0:1] offset:448
	s_add_i32 s7, s60, s10
	v_add_u32_e32 v92, s7, v92
	v_ashrrev_i32_e32 v93, 31, v92
	v_lshl_add_u64 v[102:103], v[92:93], 1, s[82:83]
	s_waitcnt vmcnt(27) lgkmcnt(3)
	v_mfma_f32_16x16x32_bf16 v[92:95], v[16:19], v[144:147], 0
	v_mul_f32_e32 v134, 0xbfb8aa3b, v143
	v_lshlrev_b32_e32 v144, 16, v126
	v_and_b32_e32 v145, 0xffff0000, v126
	v_mul_f32_e32 v126, 0xbfb8aa3b, v128
	v_exp_f32_e32 v134, v134
	v_exp_f32_e32 v135, v126
	v_mad_u64_u32 v[130:131], s[8:9], v131, s14, v[102:103]
	v_mad_i32_i24 v131, s37, v225, v131
	v_pk_add_f32 v[134:135], v[134:135], 1.0 op_sel_hi:[1,0]
	s_waitcnt vmcnt(26)
	v_mfma_f32_16x16x32_bf16 v[88:91], v[16:19], v[88:91], 0
	s_add_i32 s65, s65, s94
	s_waitcnt vmcnt(25)
	v_mfma_f32_16x16x32_bf16 v[80:83], v[16:19], v[80:83], 0
	s_add_i32 s64, s64, s68
	s_cmpk_gt_i32 s65, 0x3ff
	s_waitcnt vmcnt(0)
	v_pk_add_f32 v[92:93], v[92:93], v[132:133] op_sel_hi:[1,0]
	s_nop 0
	v_pk_mul_f32 v[92:93], v[92:93], v[144:145]
	v_rcp_f32_e32 v144, v135
	v_pk_add_f32 v[94:95], v[94:95], v[132:133] op_sel_hi:[1,0]
	s_waitcnt lgkmcnt(2)
	v_mfma_f32_16x16x32_bf16 v[80:83], v[20:23], v[84:87], v[80:83]
	v_lshlrev_b32_e32 v87, 16, v120
	v_mul_f32_e32 v126, v128, v144
	v_mov_b32_e32 v135, v126
	v_rcp_f32_e32 v128, v134
	v_mfma_f32_16x16x32_bf16 v[72:75], v[16:19], v[72:75], 0
	v_mad_u64_u32 v[84:85], s[8:9], v141, s14, v[102:103]
	v_mul_f32_e32 v126, v143, v128
	v_mov_b32_e32 v134, v126
	v_pk_mul_f32 v[92:93], v[134:135], v[92:93]
	v_lshlrev_b32_e32 v134, 16, v129
	v_and_b32_e32 v135, 0xffff0000, v129
	v_mul_f32_e32 v126, 0xbfb8aa3b, v134
	v_lshlrev_b32_e32 v128, 16, v127
	v_and_b32_e32 v129, 0xffff0000, v127
	v_mul_f32_e32 v127, 0xbfb8aa3b, v135
	v_exp_f32_e32 v126, v126
	v_exp_f32_e32 v127, v127
	v_pk_mul_f32 v[94:95], v[94:95], v[128:129]
	v_cvt_pk_bf16_f32 v92, v92, v93
	v_mad_i32_i24 v85, s37, v225, v85
	v_pk_add_f32 v[126:127], v[126:127], 1.0 op_sel_hi:[1,0]
	v_mfma_f32_16x16x32_bf16 v[72:75], v[20:23], v[76:79], v[72:75]
	v_rcp_f32_e32 v129, v127
	v_lshlrev_b32_e32 v79, 16, v116
	v_mfma_f32_16x16x32_bf16 v[60:63], v[16:19], v[60:63], 0
	v_mad_u64_u32 v[76:77], s[8:9], v140, s14, v[102:103]
	v_mul_f32_e32 v128, v135, v129
	v_mov_b32_e32 v127, v128
	v_rcp_f32_e32 v129, v126
	v_mad_i32_i24 v77, s37, v225, v77
	v_mfma_f32_16x16x32_bf16 v[60:63], v[20:23], v[64:67], v[60:63]
	v_lshlrev_b32_e32 v67, 16, v112
	v_mul_f32_e32 v128, v134, v129
	v_mov_b32_e32 v126, v128
	v_pk_mul_f32 v[94:95], v[126:127], v[94:95]
	v_lshlrev_b32_e32 v128, 16, v122
	v_cvt_pk_bf16_f32 v93, v94, v95
	global_store_dwordx2 v[130:131], v[92:93], off offset:1024
	v_lshlrev_b32_e32 v95, 16, v124
	v_and_b32_e32 v124, 0xffff0000, v124
	v_mul_f32_e32 v126, 0xbfb8aa3b, v95
	v_and_b32_e32 v129, 0xffff0000, v122
	v_mul_f32_e32 v122, 0xbfb8aa3b, v124
	v_exp_f32_e32 v126, v126
	v_exp_f32_e32 v127, v122
	v_mad_u64_u32 v[92:93], s[8:9], v142, s14, v[102:103]
	v_mad_i32_i24 v93, s37, v225, v93
	v_pk_add_f32 v[126:127], v[126:127], 1.0 op_sel_hi:[1,0]
	s_waitcnt lgkmcnt(1)
	v_mfma_f32_16x16x32_bf16 v[60:63], v[24:27], v[68:71], v[60:63]
	v_mul_f32_e32 v68, 0xbfb8aa3b, v67
	v_exp_f32_e32 v68, v68
	v_lshlrev_b32_e32 v70, 16, v110
	v_and_b32_e32 v71, 0xffff0000, v110
	v_mfma_f32_16x16x32_bf16 v[48:51], v[16:19], v[48:51], 0
	v_mad_u64_u32 v[64:65], s[8:9], v139, s14, v[102:103]
	v_mad_i32_i24 v65, s37, v225, v65
	v_mfma_f32_16x16x32_bf16 v[48:51], v[20:23], v[52:55], v[48:51]
	v_lshlrev_b32_e32 v55, 16, v108
	v_mad_u64_u32 v[52:53], s[8:9], v138, s14, v[102:103]
	v_mfma_f32_16x16x32_bf16 v[48:51], v[24:27], v[56:59], v[48:51]
	v_mul_f32_e32 v56, 0xbfb8aa3b, v55
	v_exp_f32_e32 v56, v56
	v_lshlrev_b32_e32 v58, 16, v106
	v_and_b32_e32 v59, 0xffff0000, v106
	v_mfma_f32_16x16x32_bf16 v[32:35], v[16:19], v[32:35], 0
	v_mad_i32_i24 v53, s37, v225, v53
	v_pk_add_f32 v[88:89], v[88:89], v[160:161] op_sel_hi:[1,0]
	s_nop 0
	v_pk_mul_f32 v[88:89], v[88:89], v[128:129]
	v_rcp_f32_e32 v128, v127
	v_mfma_f32_16x16x32_bf16 v[32:35], v[20:23], v[36:39], v[32:35]
	v_lshlrev_b32_e32 v39, 16, v104
	v_mad_u64_u32 v[36:37], s[8:9], v137, s14, v[102:103]
	v_mul_f32_e32 v122, v124, v128
	v_mov_b32_e32 v127, v122
	v_rcp_f32_e32 v124, v126
	v_mfma_f32_16x16x32_bf16 v[32:35], v[24:27], v[40:43], v[32:35]
	v_mul_f32_e32 v40, 0xbfb8aa3b, v39
	v_exp_f32_e32 v40, v40
	v_mul_f32_e32 v122, v95, v124
	v_mov_b32_e32 v126, v122
	v_pk_mul_f32 v[88:89], v[126:127], v[88:89]
	v_lshlrev_b32_e32 v126, 16, v125
	v_and_b32_e32 v127, 0xffff0000, v125
	v_mul_f32_e32 v95, 0xbfb8aa3b, v126
	v_pk_add_f32 v[90:91], v[90:91], v[160:161] op_sel_hi:[1,0]
	v_mul_f32_e32 v94, 0xbfb8aa3b, v127
	v_exp_f32_e32 v122, v95
	v_lshlrev_b32_e32 v124, 16, v123
	v_and_b32_e32 v125, 0xffff0000, v123
	v_exp_f32_e32 v123, v94
	v_pk_mul_f32 v[90:91], v[90:91], v[124:125]
	v_cvt_pk_bf16_f32 v88, v88, v89
	s_waitcnt lgkmcnt(0)
	v_mfma_f32_16x16x32_bf16 v[32:35], v[28:31], v[44:47], v[32:35]
	v_add_f32_e64 v94, v122, 1.0
	v_add_f32_e64 v95, v123, 1.0
	v_and_b32_e32 v44, 0xffff0000, v104
	v_rcp_f32_e32 v123, v95
	v_mul_f32_e32 v41, 0xbfb8aa3b, v44
	v_exp_f32_e32 v41, v41
	v_lshlrev_b32_e32 v42, 16, v100
	v_mul_f32_e32 v122, v127, v123
	v_mov_b32_e32 v95, v122
	v_rcp_f32_e32 v123, v94
	v_and_b32_e32 v43, 0xffff0000, v100
	v_pk_add_f32 v[40:41], v[40:41], 1.0 op_sel_hi:[1,0]
	v_mfma_f32_16x16x32_bf16 v[0:3], v[16:19], v[0:3], 0
	v_mul_f32_e32 v122, v126, v123
	v_mov_b32_e32 v94, v122
	v_pk_mul_f32 v[90:91], v[94:95], v[90:91]
	v_mad_i32_i24 v37, s37, v225, v37
	v_cvt_pk_bf16_f32 v89, v90, v91
	global_store_dwordx2 v[92:93], v[88:89], off offset:1024
	v_and_b32_e32 v92, 0xffff0000, v120
	v_mul_f32_e32 v88, 0xbfb8aa3b, v87
	v_mul_f32_e32 v89, 0xbfb8aa3b, v92
	v_exp_f32_e32 v88, v88
	v_exp_f32_e32 v89, v89
	v_lshlrev_b32_e32 v90, 16, v118
	v_and_b32_e32 v91, 0xffff0000, v118
	v_mfma_f32_16x16x32_bf16 v[0:3], v[20:23], v[4:7], v[0:3]
	v_add_f32_e64 v88, v88, 1.0
	v_add_f32_e64 v89, v89, 1.0
	v_lshlrev_b32_e32 v7, 16, v98
	v_mad_u64_u32 v[4:5], s[8:9], v133, s14, v[102:103]
	v_mfma_f32_16x16x32_bf16 v[0:3], v[24:27], v[8:11], v[0:3]
	v_mul_f32_e32 v8, 0xbfb8aa3b, v7
	v_exp_f32_e32 v8, v8
	v_lshlrev_b32_e32 v10, 16, v96
	v_mfma_f32_16x16x32_bf16 v[0:3], v[28:31], v[12:15], v[0:3]
	v_and_b32_e32 v12, 0xffff0000, v98
	v_mul_f32_e32 v9, 0xbfb8aa3b, v12
	v_exp_f32_e32 v9, v9
	v_and_b32_e32 v11, 0xffff0000, v96
	v_mad_i32_i24 v5, s37, v225, v5
	v_pk_add_f32 v[8:9], v[8:9], 1.0 op_sel_hi:[1,0]
	v_pk_add_f32 v[80:81], v[80:81], v[162:163] op_sel_hi:[1,0]
	s_nop 0
	v_pk_mul_f32 v[80:81], v[80:81], v[90:91]
	v_rcp_f32_e32 v91, v89
	s_nop 0
	v_mul_f32_e32 v90, v92, v91
	v_mov_b32_e32 v89, v90
	v_rcp_f32_e32 v91, v88
	s_nop 0
	v_mul_f32_e32 v90, v87, v91
	v_lshlrev_b32_e32 v92, 16, v121
	v_mov_b32_e32 v88, v90
	v_and_b32_e32 v93, 0xffff0000, v121
	v_mul_f32_e32 v87, 0xbfb8aa3b, v92
	v_pk_add_f32 v[82:83], v[82:83], v[162:163] op_sel_hi:[1,0]
	v_mul_f32_e32 v86, 0xbfb8aa3b, v93
	v_pk_mul_f32 v[80:81], v[88:89], v[80:81]
	v_exp_f32_e32 v88, v87
	v_exp_f32_e32 v89, v86
	v_lshlrev_b32_e32 v90, 16, v119
	v_and_b32_e32 v91, 0xffff0000, v119
	v_pk_mul_f32 v[82:83], v[82:83], v[90:91]
	v_pk_add_f32 v[86:87], v[88:89], 1.0 op_sel_hi:[1,0]
	v_cvt_pk_bf16_f32 v80, v80, v81
	v_rcp_f32_e32 v89, v87
	s_nop 0
	v_mul_f32_e32 v88, v93, v89
	v_mov_b32_e32 v87, v88
	v_rcp_f32_e32 v89, v86
	s_nop 0
	v_mul_f32_e32 v88, v92, v89
	v_mov_b32_e32 v86, v88
	v_pk_mul_f32 v[82:83], v[86:87], v[82:83]
	s_nop 0
	v_cvt_pk_bf16_f32 v81, v82, v83
	global_store_dwordx2 v[84:85], v[80:81], off offset:1024
	v_and_b32_e32 v84, 0xffff0000, v116
	v_mul_f32_e32 v80, 0xbfb8aa3b, v79
	v_mul_f32_e32 v81, 0xbfb8aa3b, v84
	v_exp_f32_e32 v80, v80
	v_exp_f32_e32 v81, v81
	v_lshlrev_b32_e32 v82, 16, v114
	v_and_b32_e32 v83, 0xffff0000, v114
	v_pk_add_f32 v[80:81], v[80:81], 1.0 op_sel_hi:[1,0]
	v_pk_add_f32 v[72:73], v[72:73], v[164:165] op_sel_hi:[1,0]
	s_nop 0
	v_pk_mul_f32 v[72:73], v[72:73], v[82:83]
	v_rcp_f32_e32 v83, v81
	s_nop 0
	v_mul_f32_e32 v82, v84, v83
	v_mov_b32_e32 v81, v82
	v_rcp_f32_e32 v83, v80
	s_nop 0
	v_mul_f32_e32 v82, v79, v83
	v_lshlrev_b32_e32 v84, 16, v117
	v_mov_b32_e32 v80, v82
	v_and_b32_e32 v85, 0xffff0000, v117
	v_mul_f32_e32 v79, 0xbfb8aa3b, v84
	v_pk_add_f32 v[74:75], v[74:75], v[164:165] op_sel_hi:[1,0]
	v_mul_f32_e32 v78, 0xbfb8aa3b, v85
	v_pk_mul_f32 v[72:73], v[80:81], v[72:73]
	v_exp_f32_e32 v80, v79
	v_exp_f32_e32 v81, v78
	v_lshlrev_b32_e32 v82, 16, v115
	v_and_b32_e32 v83, 0xffff0000, v115
	v_pk_mul_f32 v[74:75], v[74:75], v[82:83]
	v_pk_add_f32 v[78:79], v[80:81], 1.0 op_sel_hi:[1,0]
	v_cvt_pk_bf16_f32 v72, v72, v73
	v_rcp_f32_e32 v81, v79
	s_nop 0
	v_mul_f32_e32 v80, v85, v81
	v_mov_b32_e32 v79, v80
	v_rcp_f32_e32 v81, v78
	s_nop 0
	v_mul_f32_e32 v80, v84, v81
	v_mov_b32_e32 v78, v80
	v_pk_mul_f32 v[74:75], v[78:79], v[74:75]
	s_nop 0
	v_cvt_pk_bf16_f32 v73, v74, v75
	global_store_dwordx2 v[76:77], v[72:73], off offset:1024
	v_and_b32_e32 v72, 0xffff0000, v112
	v_mul_f32_e32 v69, 0xbfb8aa3b, v72
	v_exp_f32_e32 v69, v69
	v_pk_add_f32 v[60:61], v[60:61], v[166:167] op_sel_hi:[1,0]
	v_pk_add_f32 v[68:69], v[68:69], 1.0 op_sel_hi:[1,0]
	v_pk_mul_f32 v[60:61], v[60:61], v[70:71]
	v_rcp_f32_e32 v71, v69
	s_nop 0
	v_mul_f32_e32 v70, v72, v71
	v_mov_b32_e32 v69, v70
	v_rcp_f32_e32 v71, v68
	s_nop 0
	v_mul_f32_e32 v70, v67, v71
	v_lshlrev_b32_e32 v72, 16, v113
	v_mov_b32_e32 v68, v70
	v_and_b32_e32 v73, 0xffff0000, v113
	v_mul_f32_e32 v67, 0xbfb8aa3b, v72
	v_pk_add_f32 v[62:63], v[62:63], v[166:167] op_sel_hi:[1,0]
	v_mul_f32_e32 v66, 0xbfb8aa3b, v73
	v_pk_mul_f32 v[60:61], v[68:69], v[60:61]
	v_exp_f32_e32 v68, v67
	v_exp_f32_e32 v69, v66
	v_lshlrev_b32_e32 v70, 16, v111
	v_and_b32_e32 v71, 0xffff0000, v111
	v_pk_mul_f32 v[62:63], v[62:63], v[70:71]
	v_pk_add_f32 v[66:67], v[68:69], 1.0 op_sel_hi:[1,0]
	v_cvt_pk_bf16_f32 v60, v60, v61
	v_rcp_f32_e32 v69, v67
	s_nop 0
	v_mul_f32_e32 v68, v73, v69
	v_mov_b32_e32 v67, v68
	v_rcp_f32_e32 v69, v66
	s_nop 0
	v_mul_f32_e32 v68, v72, v69
	v_mov_b32_e32 v66, v68
	v_pk_mul_f32 v[62:63], v[66:67], v[62:63]
	s_nop 0
	v_cvt_pk_bf16_f32 v61, v62, v63
	global_store_dwordx2 v[64:65], v[60:61], off offset:1024
	v_and_b32_e32 v60, 0xffff0000, v108
	v_mul_f32_e32 v57, 0xbfb8aa3b, v60
	v_exp_f32_e32 v57, v57
	v_pk_add_f32 v[48:49], v[48:49], v[168:169] op_sel_hi:[1,0]
	v_pk_add_f32 v[56:57], v[56:57], 1.0 op_sel_hi:[1,0]
	v_pk_mul_f32 v[48:49], v[48:49], v[58:59]
	v_rcp_f32_e32 v59, v57
	s_nop 0
	v_mul_f32_e32 v58, v60, v59
	v_mov_b32_e32 v57, v58
	v_rcp_f32_e32 v59, v56
	s_nop 0
	v_mul_f32_e32 v58, v55, v59
	v_lshlrev_b32_e32 v60, 16, v109
	v_mov_b32_e32 v56, v58
	v_and_b32_e32 v61, 0xffff0000, v109
	v_mul_f32_e32 v55, 0xbfb8aa3b, v60
	v_pk_add_f32 v[50:51], v[50:51], v[168:169] op_sel_hi:[1,0]
	v_mul_f32_e32 v54, 0xbfb8aa3b, v61
	v_pk_mul_f32 v[48:49], v[56:57], v[48:49]
	v_exp_f32_e32 v56, v55
	v_exp_f32_e32 v57, v54
	v_lshlrev_b32_e32 v58, 16, v107
	v_and_b32_e32 v59, 0xffff0000, v107
	v_pk_mul_f32 v[50:51], v[50:51], v[58:59]
	v_pk_add_f32 v[54:55], v[56:57], 1.0 op_sel_hi:[1,0]
	v_cvt_pk_bf16_f32 v48, v48, v49
	v_rcp_f32_e32 v57, v55
	s_nop 0
	v_mul_f32_e32 v56, v61, v57
	v_mov_b32_e32 v55, v56
	v_rcp_f32_e32 v57, v54
	s_nop 0
	v_mul_f32_e32 v56, v60, v57
	v_mov_b32_e32 v54, v56
	v_pk_mul_f32 v[50:51], v[54:55], v[50:51]
	s_nop 0
	v_cvt_pk_bf16_f32 v49, v50, v51
	global_store_dwordx2 v[52:53], v[48:49], off offset:1024
	v_pk_add_f32 v[32:33], v[32:33], v[170:171] op_sel_hi:[1,0]
	s_nop 0
	v_pk_mul_f32 v[32:33], v[32:33], v[42:43]
	v_rcp_f32_e32 v43, v41
	s_nop 0
	v_mul_f32_e32 v42, v44, v43
	v_mov_b32_e32 v41, v42
	v_rcp_f32_e32 v43, v40
	s_nop 0
	v_mul_f32_e32 v42, v39, v43
	v_lshlrev_b32_e32 v44, 16, v105
	v_mov_b32_e32 v40, v42
	v_and_b32_e32 v45, 0xffff0000, v105
	v_mul_f32_e32 v39, 0xbfb8aa3b, v44
	v_pk_add_f32 v[34:35], v[34:35], v[170:171] op_sel_hi:[1,0]
	v_mul_f32_e32 v38, 0xbfb8aa3b, v45
	v_pk_mul_f32 v[32:33], v[40:41], v[32:33]
	v_exp_f32_e32 v40, v39
	v_exp_f32_e32 v41, v38
	v_lshlrev_b32_e32 v42, 16, v101
	v_and_b32_e32 v43, 0xffff0000, v101
	v_pk_mul_f32 v[34:35], v[34:35], v[42:43]
	v_pk_add_f32 v[38:39], v[40:41], 1.0 op_sel_hi:[1,0]
	v_cvt_pk_bf16_f32 v32, v32, v33
	v_rcp_f32_e32 v41, v39
	s_nop 0
	v_mul_f32_e32 v40, v45, v41
	v_mov_b32_e32 v39, v40
	v_rcp_f32_e32 v41, v38
	s_nop 0
	v_mul_f32_e32 v40, v44, v41
	v_mov_b32_e32 v38, v40
	v_pk_mul_f32 v[34:35], v[38:39], v[34:35]
	s_nop 0
	v_cvt_pk_bf16_f32 v33, v34, v35
	global_store_dwordx2 v[36:37], v[32:33], off offset:1024
	v_pk_add_f32 v[0:1], v[0:1], v[172:173] op_sel_hi:[1,0]
	s_nop 0
	v_pk_mul_f32 v[0:1], v[0:1], v[10:11]
	v_rcp_f32_e32 v11, v9
	s_nop 0
	v_mul_f32_e32 v10, v12, v11
	v_mov_b32_e32 v9, v10
	v_rcp_f32_e32 v11, v8
	s_nop 0
	v_mul_f32_e32 v10, v7, v11
	v_lshlrev_b32_e32 v12, 16, v99
	v_mov_b32_e32 v8, v10
	v_and_b32_e32 v13, 0xffff0000, v99
	v_mul_f32_e32 v7, 0xbfb8aa3b, v12
	v_pk_add_f32 v[2:3], v[2:3], v[172:173] op_sel_hi:[1,0]
	v_mul_f32_e32 v6, 0xbfb8aa3b, v13
	v_pk_mul_f32 v[0:1], v[8:9], v[0:1]
	v_exp_f32_e32 v8, v7
	v_exp_f32_e32 v9, v6
	v_lshlrev_b32_e32 v10, 16, v97
	v_and_b32_e32 v11, 0xffff0000, v97
	v_pk_mul_f32 v[2:3], v[2:3], v[10:11]
	v_pk_add_f32 v[6:7], v[8:9], 1.0 op_sel_hi:[1,0]
	v_cvt_pk_bf16_f32 v0, v0, v1
	v_rcp_f32_e32 v9, v7
	s_nop 0
	v_mul_f32_e32 v8, v13, v9
	v_mov_b32_e32 v7, v8
	v_rcp_f32_e32 v9, v6
	s_nop 0
	v_mul_f32_e32 v8, v12, v9
	v_mov_b32_e32 v6, v8
	v_pk_mul_f32 v[2:3], v[6:7], v[2:3]
	s_nop 0
	v_cvt_pk_bf16_f32 v1, v2, v3
	global_store_dwordx2 v[4:5], v[0:1], off offset:1024
	s_barrier
	s_cbranch_scc0 .LBB0_825
